# kept configuration + layer-dependent GEMM1 unit order (the cheap-tile exchange only in layer 1; in layer 0 the 7-unit workgroups carry the longer conversion tail)
# speedup vs baseline: 1.0098x; 1.0045x over previous
;     __host__ __device__ bool next(int i, Unit& u) const {
;     ...
;         int wgid = (int)L; { const int q = nwg / NXCD, r = nwg % NXCD, xcd = wgid % NXCD; int off = wgid / NXCD;
;             if (G == 256 && nwg == 1920 && ((off >> 5) == 1 || (off >> 5) == 5)) off ^= 16;
;             wgid = (xcd < r ? xcd * (q + 1) : r * (q + 1) + (xcd - r) * q) + off; }
.LBB0_283:
	s_andn2_b64 vcc, exec, s[34:35]
	s_cbranch_vccnz .LBB0_285
	s_cmp_eq_u32 s10, 8
	s_cselect_b32 s34, 16, 0
	s_xor_b32 s3, s3, s34

;     __host__ __device__ bool next(int i, Unit& u) const {
;         const long L = (long)i * G + c; if (L >= nwg) return false;
;         int wgid = (int)L; { const int q = nwg / NXCD, r = nwg % NXCD, xcd = wgid % NXCD; int off = wgid / NXCD;
;             if (G == 256 && nwg == 1920 && ((off >> 5) == 1 || (off >> 5) == 5)) off ^= 16;
;             wgid = (xcd < r ? xcd * (q + 1) : r * (q + 1) + (xcd - r) * q) + off; }
;         const int nig = WGM * nN, gid = wgid / nig, fm = gid * WGM, gsz = (nM - fm) < WGM ? (nM - fm) : WGM;
;         u.pm = fm + ((wgid % nig) % gsz); u.pn = (wgid % nig) / gsz; return true;
;     }
.LBB0_298:
	s_andn2_b64 vcc, exec, s[54:55]
	s_mov_b32 s30, s22
	s_cbranch_vccnz .LBB0_300
	s_cmp_eq_u32 s10, 8
	s_cselect_b32 s54, 16, 0
	s_xor_b32 s30, s22, s54
